# v10: v5 + indexer scoring loop pipelined (3-buffer ring, fragment prefetch) + waves 4-7 offset by ~256 cycles after each barrier
# baseline (speedup 1.0000x reference)
.LBB0_105:
	s_lshl_b32 s1, s21, 4
	s_and_b32 s2, s1, 0x7f0
	s_and_b32 s0, s21, 0x100
	s_xor_b32 s6, s2, 0x7f0
	s_cmp_eq_u32 s0, 0
	s_cselect_b32 s2, s2, s6
	s_add_i32 s10, s2, s17
	s_and_b32 s33, s1, 0xfffff800
	s_add_i32 s6, s10, s33
	v_or_b32_e32 v2, s6, v249
	v_ashrrev_i32_e32 v3, 31, v2
	v_lshlrev_b64 v[2:3], 11, v[2:3]
	s_ashr_i32 s7, s6, 31
	v_lshl_add_u64 v[2:3], v[232:233], 0, v[2:3]
	s_lshl_b64 s[0:1], s[6:7], 6
	global_load_dwordx4 v[34:37], v[2:3], off
	global_load_dwordx4 v[38:41], v[2:3], off offset:32
	global_load_dwordx4 v[42:45], v[2:3], off offset:64
	global_load_dwordx4 v[46:49], v[2:3], off offset:96
	v_lshl_add_u64 v[2:3], v[238:239], 0, s[0:1]
	v_writelane_b32 v254, s6, 35
	s_or_b32 s0, s6, 1
	s_ashr_i32 s1, s0, 31
	s_lshl_b64 s[0:1], s[0:1], 6
	global_load_dwordx4 v[50:53], v[2:3], off
	global_load_dwordx4 v[54:57], v[2:3], off offset:32
	v_lshl_add_u64 v[2:3], v[238:239], 0, s[0:1]
	global_load_dwordx4 v[58:61], v[2:3], off
	global_load_dwordx4 v[62:65], v[2:3], off offset:32
	s_lshr_b32 s0, s2, 5
	s_add_i32 s0, s0, 2
	v_or_b32_e32 v2, s33, v248
	s_lshr_b32 s8, s0, 1
	v_ashrrev_i32_e32 v3, 31, v2
	s_add_i32 s9, s8, -1
	v_lshlrev_b64 v[2:3], 7, v[2:3]
	s_cmp_gt_u32 s2, 48
	v_lshl_add_u64 v[240:241], v[234:235], 0, v[2:3]
	s_cselect_b32 s2, 0x2000, 0
	v_lshl_add_u64 v[2:3], v[240:241], 0, s[2:3]
	s_movk_i32 s0, 0x1000
	v_add_co_u32_e32 v4, vcc, s0, v2
	v_writelane_b32 v254, s7, 36
	s_nop 0
	v_addc_co_u32_e32 v5, vcc, 0, v3, vcc
	v_add_co_u32_e32 v6, vcc, 0x1000, v240
	s_mov_b32 s2, 4
	s_nop 0
	v_addc_co_u32_e32 v7, vcc, 0, v241, vcc
	v_mov_b32_e32 v251, v250
	v_mov_b32_e32 v0, v245
	s_waitcnt vmcnt(0)
	s_waitcnt vmcnt(6)
	s_waitcnt vmcnt(5)
	s_waitcnt vmcnt(4)
	s_waitcnt vmcnt(3)
	s_waitcnt vmcnt(2)
	s_waitcnt vmcnt(1)
	s_waitcnt vmcnt(0)
	v_readlane_b32 s0, v253, 23
	s_lshl_b32 s1, s33, 7
	s_nop 3
	s_lshl_b32 s0, s0, 10
	v_lshl_add_u32 v138, v178, 4, s0
	s_add_u32 s6, s22, 0x32600000
	s_addc_u32 s7, s23, 0
	s_add_u32 s6, s6, s1
	s_addc_u32 s7, s7, 0
	v_mov_b32_e32 v139, 0
	v_lshl_add_u64 v[134:135], s[6:7], 0, v[138:139]
	s_movk_i32 s12, 0x90
	v_lshrrev_b32_e32 v140, 7, v138
	v_and_b32_e32 v141, 0x70, v138
	v_mad_u32_u24 v136, v140, s12, v141
	v_add_u32_e32 v136, 0x20200, v136
	v_lshrrev_b32_e32 v140, 5, v178
	v_lshlrev_b32_e32 v140, 4, v140
	v_mad_u32_u24 v137, v248, s12, v140
	v_add_u32_e32 v137, 0x20200, v137
	s_mov_b32 s12, 0x2000
	s_mov_b32 s13, 0
	s_mov_b32 s2, 0
	v_readlane_b32 s1, v253, 23
	s_nop 3
	s_lshr_b32 s1, s1, 2
	global_load_dwordx4 v[130:133], v[134:135], off
	v_lshl_add_u64 v[134:135], v[134:135], 0, s[12:13]
	s_waitcnt vmcnt(0)
	ds_write_b128 v136, v[130:133]
	s_waitcnt lgkmcnt(0)
	s_cmp_lt_u32 s8, 2
	s_cbranch_scc1 .Lidx_pro_done
	global_load_dwordx4 v[130:133], v[134:135], off
	v_lshl_add_u64 v[134:135], v[134:135], 0, s[12:13]
	s_waitcnt vmcnt(0)
	ds_write_b128 v136, v[130:133] offset:9216
	s_waitcnt lgkmcnt(0)
	s_cmp_lt_u32 s8, 3
	s_cbranch_scc1 .Lidx_pro_done
	global_load_dwordx4 v[130:133], v[134:135], off
	v_lshl_add_u64 v[134:135], v[134:135], 0, s[12:13]
.Lidx_pro_done:
	s_barrier
	s_cmp_eq_u32 s1, 0
	s_cbranch_scc1 .Lidx_nosleep0
	s_sleep 4
.Lidx_nosleep0:
	ds_read_b128 v[118:121], v137
	ds_read_b128 v[126:129], v137 offset:4608
	ds_read_b128 v[114:117], v137 offset:32
	ds_read_b128 v[122:125], v137 offset:4640
	ds_read_b128 v[110:113], v137 offset:64
	ds_read_b128 v[106:109], v137 offset:4672
	ds_read_b128 v[102:105], v137 offset:96
	ds_read_b128 v[86:89], v137 offset:4704
	s_waitcnt lgkmcnt(0)
	s_mov_b32 s11, 0x2400
	s_mov_b32 s9, 0x4800
.Lidx_body0:
	s_add_i32 s0, s2, 1
	s_cmp_ge_u32 s0, s8
	s_cbranch_scc1 .Lidx_nord0
	v_add_u32_e32 v138, s11, v137
	ds_read_b128 v[90:93], v138
	ds_read_b128 v[98:101], v138 offset:4608
	ds_read_b128 v[78:81], v138 offset:32
	ds_read_b128 v[94:97], v138 offset:4640
	ds_read_b128 v[74:77], v138 offset:64
	ds_read_b128 v[82:85], v138 offset:4672
	ds_read_b128 v[70:73], v138 offset:96
	ds_read_b128 v[66:69], v138 offset:4704
.Lidx_nord0:
	v_mfma_f32_32x32x16_bf16 v[18:33], v[34:37], v[118:121], 0
	v_mfma_f32_32x32x16_bf16 v[2:17], v[34:37], v[126:129], 0
	v_mfma_f32_32x32x16_bf16 v[18:33], v[38:41], v[114:117], v[18:33]
	v_mfma_f32_32x32x16_bf16 v[2:17], v[38:41], v[122:125], v[2:17]
	v_mfma_f32_32x32x16_bf16 v[18:33], v[42:45], v[110:113], v[18:33]
	v_mfma_f32_32x32x16_bf16 v[2:17], v[42:45], v[106:109], v[2:17]
	v_mfma_f32_32x32x16_bf16 v[2:17], v[46:49], v[86:89], v[2:17]
	v_mfma_f32_32x32x16_bf16 v[18:33], v[46:49], v[102:105], v[18:33]
	s_nop 10
	v_max_i32_e32 v2, 0, v2
	v_fma_f32 v2, v50, v2, 0
	v_max_i32_e32 v10, 0, v10
	v_max_i32_e32 v3, 0, v3
	v_fma_f32 v10, v58, v10, 0
	v_fmac_f32_e32 v2, v51, v3
	v_max_i32_e32 v3, 0, v11
	v_max_i32_e32 v18, 0, v18
	v_fma_f32 v18, v50, v18, 0
	v_max_i32_e32 v26, 0, v26
	v_max_i32_e32 v19, 0, v19
	v_fma_f32 v26, v58, v26, 0
	v_fmac_f32_e32 v18, v51, v19
	v_max_i32_e32 v19, 0, v27
	v_fmac_f32_e32 v10, v59, v3
	v_max_i32_e32 v3, 0, v20
	v_fmac_f32_e32 v26, v59, v19
	v_fmac_f32_e32 v18, v52, v3
	v_max_i32_e32 v3, 0, v28
	v_fmac_f32_e32 v26, v60, v3
	v_max_i32_e32 v3, 0, v4
	v_fmac_f32_e32 v2, v52, v3
	v_max_i32_e32 v3, 0, v12
	v_fmac_f32_e32 v10, v60, v3
	v_max_i32_e32 v3, 0, v21
	v_fmac_f32_e32 v18, v53, v3
	v_max_i32_e32 v3, 0, v29
	v_fmac_f32_e32 v26, v61, v3
	v_max_i32_e32 v3, 0, v5
	v_fmac_f32_e32 v2, v53, v3
	v_max_i32_e32 v3, 0, v13
	v_fmac_f32_e32 v10, v61, v3
	v_max_i32_e32 v3, 0, v22
	v_fmac_f32_e32 v18, v54, v3
	v_max_i32_e32 v3, 0, v30
	v_fmac_f32_e32 v26, v62, v3
	v_max_i32_e32 v3, 0, v6
	v_fmac_f32_e32 v2, v54, v3
	v_max_i32_e32 v3, 0, v14
	v_fmac_f32_e32 v10, v62, v3
	v_max_i32_e32 v3, 0, v23
	v_fmac_f32_e32 v18, v55, v3
	v_max_i32_e32 v3, 0, v31
	v_fmac_f32_e32 v26, v63, v3
	v_max_i32_e32 v3, 0, v7
	v_fmac_f32_e32 v2, v55, v3
	v_max_i32_e32 v3, 0, v15
	v_fmac_f32_e32 v10, v63, v3
	v_max_i32_e32 v3, 0, v24
	v_fmac_f32_e32 v18, v56, v3
	v_max_i32_e32 v3, 0, v32
	v_fmac_f32_e32 v26, v64, v3
	v_max_i32_e32 v3, 0, v8
	v_fmac_f32_e32 v2, v56, v3
	v_max_i32_e32 v3, 0, v16
	v_fmac_f32_e32 v10, v64, v3
	v_max_i32_e32 v3, 0, v25
	v_fmac_f32_e32 v18, v57, v3
	v_max_i32_e32 v3, 0, v33
	v_fmac_f32_e32 v26, v65, v3
	v_max_i32_e32 v3, 0, v9
	v_fmac_f32_e32 v2, v57, v3
	v_max_i32_e32 v3, 0, v17
	v_fmac_f32_e32 v10, v65, v3
	v_mov_b32_e32 v3, v18
	v_mov_b32_e32 v5, v26
	v_mov_b32_e32 v4, v2
	v_mov_b32_e32 v6, v10
	v_permlane32_swap_b32_e32 v18, v3
	v_permlane32_swap_b32_e32 v26, v5
	v_permlane32_swap_b32_e32 v2, v4
	v_permlane32_swap_b32_e32 v10, v6
	s_and_saveexec_b64 s[6:7], s[4:5]
	s_xor_b64 s[6:7], exec, s[6:7]
	v_add_f32_e32 v2, v10, v6
	v_add_f32_e32 v3, v26, v5
	ds_write2_b32 v0, v3, v2 offset1:32
	s_andn2_saveexec_b64 s[6:7], s[6:7]
	v_add_f32_e32 v2, v2, v4
	v_add_f32_e32 v3, v18, v3
	ds_write2_b32 v251, v3, v2 offset1:32
	s_or_b64 exec, exec, s[6:7]
	v_add_u32_e32 v0, 0x100, v0
	v_add_u32_e32 v251, 0x100, v251
	s_add_i32 s0, s2, 2
	s_cmp_ge_u32 s0, s8
	s_cbranch_scc1 .Lidx_nost0
	s_waitcnt vmcnt(0)
	v_add_u32_e32 v138, s9, v136
	ds_write_b128 v138, v[130:133]
.Lidx_nost0:
	s_waitcnt lgkmcnt(0)
	s_add_i32 s0, s2, 3
	s_cmp_ge_u32 s0, s8
	s_cbranch_scc1 .Lidx_nold0
	global_load_dwordx4 v[130:133], v[134:135], off
	v_lshl_add_u64 v[134:135], v[134:135], 0, s[12:13]
.Lidx_nold0:
	s_add_i32 s11, s11, 0x2400
	s_cmp_eq_u32 s11, 0x6c00
	s_cselect_b32 s11, 0, s11
	s_add_i32 s9, s9, 0x2400
	s_cmp_eq_u32 s9, 0x6c00
	s_cselect_b32 s9, 0, s9
	s_add_i32 s2, s2, 1
	s_cmp_ge_u32 s2, s8
	s_cbranch_scc1 .Lidx_done
	s_barrier
	s_cmp_eq_u32 s1, 0
	s_cbranch_scc1 .Lidx_nosleep1
	s_sleep 4
.Lidx_nosleep1:
.Lidx_body1:
	s_add_i32 s0, s2, 1
	s_cmp_ge_u32 s0, s8
	s_cbranch_scc1 .Lidx_nord1
	v_add_u32_e32 v138, s11, v137
	ds_read_b128 v[118:121], v138
	ds_read_b128 v[126:129], v138 offset:4608
	ds_read_b128 v[114:117], v138 offset:32
	ds_read_b128 v[122:125], v138 offset:4640
	ds_read_b128 v[110:113], v138 offset:64
	ds_read_b128 v[106:109], v138 offset:4672
	ds_read_b128 v[102:105], v138 offset:96
	ds_read_b128 v[86:89], v138 offset:4704
.Lidx_nord1:
	v_mfma_f32_32x32x16_bf16 v[18:33], v[34:37], v[90:93], 0
	v_mfma_f32_32x32x16_bf16 v[2:17], v[34:37], v[98:101], 0
	v_mfma_f32_32x32x16_bf16 v[18:33], v[38:41], v[78:81], v[18:33]
	v_mfma_f32_32x32x16_bf16 v[2:17], v[38:41], v[94:97], v[2:17]
	v_mfma_f32_32x32x16_bf16 v[18:33], v[42:45], v[74:77], v[18:33]
	v_mfma_f32_32x32x16_bf16 v[2:17], v[42:45], v[82:85], v[2:17]
	v_mfma_f32_32x32x16_bf16 v[2:17], v[46:49], v[66:69], v[2:17]
	v_mfma_f32_32x32x16_bf16 v[18:33], v[46:49], v[70:73], v[18:33]
	s_nop 10
	v_max_i32_e32 v2, 0, v2
	v_fma_f32 v2, v50, v2, 0
	v_max_i32_e32 v10, 0, v10
	v_max_i32_e32 v3, 0, v3
	v_fma_f32 v10, v58, v10, 0
	v_fmac_f32_e32 v2, v51, v3
	v_max_i32_e32 v3, 0, v11
	v_max_i32_e32 v18, 0, v18
	v_fma_f32 v18, v50, v18, 0
	v_max_i32_e32 v26, 0, v26
	v_max_i32_e32 v19, 0, v19
	v_fma_f32 v26, v58, v26, 0
	v_fmac_f32_e32 v18, v51, v19
	v_max_i32_e32 v19, 0, v27
	v_fmac_f32_e32 v10, v59, v3
	v_max_i32_e32 v3, 0, v20
	v_fmac_f32_e32 v26, v59, v19
	v_fmac_f32_e32 v18, v52, v3
	v_max_i32_e32 v3, 0, v28
	v_fmac_f32_e32 v26, v60, v3
	v_max_i32_e32 v3, 0, v4
	v_fmac_f32_e32 v2, v52, v3
	v_max_i32_e32 v3, 0, v12
	v_fmac_f32_e32 v10, v60, v3
	v_max_i32_e32 v3, 0, v21
	v_fmac_f32_e32 v18, v53, v3
	v_max_i32_e32 v3, 0, v29
	v_fmac_f32_e32 v26, v61, v3
	v_max_i32_e32 v3, 0, v5
	v_fmac_f32_e32 v2, v53, v3
	v_max_i32_e32 v3, 0, v13
	v_fmac_f32_e32 v10, v61, v3
	v_max_i32_e32 v3, 0, v22
	v_fmac_f32_e32 v18, v54, v3
	v_max_i32_e32 v3, 0, v30
	v_fmac_f32_e32 v26, v62, v3
	v_max_i32_e32 v3, 0, v6
	v_fmac_f32_e32 v2, v54, v3
	v_max_i32_e32 v3, 0, v14
	v_fmac_f32_e32 v10, v62, v3
	v_max_i32_e32 v3, 0, v23
	v_fmac_f32_e32 v18, v55, v3
	v_max_i32_e32 v3, 0, v31
	v_fmac_f32_e32 v26, v63, v3
	v_max_i32_e32 v3, 0, v7
	v_fmac_f32_e32 v2, v55, v3
	v_max_i32_e32 v3, 0, v15
	v_fmac_f32_e32 v10, v63, v3
	v_max_i32_e32 v3, 0, v24
	v_fmac_f32_e32 v18, v56, v3
	v_max_i32_e32 v3, 0, v32
	v_fmac_f32_e32 v26, v64, v3
	v_max_i32_e32 v3, 0, v8
	v_fmac_f32_e32 v2, v56, v3
	v_max_i32_e32 v3, 0, v16
	v_fmac_f32_e32 v10, v64, v3
	v_max_i32_e32 v3, 0, v25
	v_fmac_f32_e32 v18, v57, v3
	v_max_i32_e32 v3, 0, v33
	v_fmac_f32_e32 v26, v65, v3
	v_max_i32_e32 v3, 0, v9
	v_fmac_f32_e32 v2, v57, v3
	v_max_i32_e32 v3, 0, v17
	v_fmac_f32_e32 v10, v65, v3
	v_mov_b32_e32 v3, v18
	v_mov_b32_e32 v5, v26
	v_mov_b32_e32 v4, v2
	v_mov_b32_e32 v6, v10
	v_permlane32_swap_b32_e32 v18, v3
	v_permlane32_swap_b32_e32 v26, v5
	v_permlane32_swap_b32_e32 v2, v4
	v_permlane32_swap_b32_e32 v10, v6
	s_and_saveexec_b64 s[6:7], s[4:5]
	s_xor_b64 s[6:7], exec, s[6:7]
	v_add_f32_e32 v2, v10, v6
	v_add_f32_e32 v3, v26, v5
	ds_write2_b32 v0, v3, v2 offset1:32
	s_andn2_saveexec_b64 s[6:7], s[6:7]
	v_add_f32_e32 v2, v2, v4
	v_add_f32_e32 v3, v18, v3
	ds_write2_b32 v251, v3, v2 offset1:32
	s_or_b64 exec, exec, s[6:7]
	v_add_u32_e32 v0, 0x100, v0
	v_add_u32_e32 v251, 0x100, v251
	s_add_i32 s0, s2, 2
	s_cmp_ge_u32 s0, s8
	s_cbranch_scc1 .Lidx_nost1
	s_waitcnt vmcnt(0)
	v_add_u32_e32 v138, s9, v136
	ds_write_b128 v138, v[130:133]

.Lidx_nosleep2:
	s_branch .Lidx_body0
.Lidx_done:
	s_barrier
.LBB0_123:
	ds_read2st64_b32 v[4:5], v250 offset1:1
	ds_read2st64_b32 v[6:7], v250 offset0:32 offset1:33
	ds_read2st64_b32 v[8:9], v250 offset0:2 offset1:3
	ds_read2st64_b32 v[12:13], v250 offset0:4 offset1:5
	ds_read2st64_b32 v[16:17], v250 offset0:6 offset1:7
	s_waitcnt lgkmcnt(4)
	v_and_b32_e32 v3, 0x7fffffff, v4
	s_waitcnt lgkmcnt(3)
	v_and_b32_e32 v2, 0x7fffffff, v6
	v_xor_b32_e32 v20, -1, v6
	v_pk_add_f32 v[2:3], v[2:3], 0 neg_lo:[1,1] neg_hi:[1,1]
	v_cmp_gt_i32_e32 vcc, 0, v6
	v_xor_b32_e32 v0, -1, v4
	s_or_b32 s2, s10, 1
	v_cndmask_b32_e32 v6, v2, v20, vcc
	v_cmp_gt_i32_e32 vcc, 0, v4
	v_and_b32_e32 v21, 0x7fffffff, v5
	v_and_b32_e32 v20, 0x7fffffff, v7
	v_cndmask_b32_e32 v0, v3, v0, vcc
	v_cmp_ge_i32_e32 vcc, s10, v229
	v_xor_b32_e32 v4, -1, v7
	v_pk_add_f32 v[20:21], v[20:21], 0 neg_lo:[1,1] neg_hi:[1,1]
	v_cndmask_b32_e32 v2, 0, v0, vcc
	v_cmp_ge_i32_e32 vcc, s2, v178
	ds_read2st64_b32 v[10:11], v250 offset0:34 offset1:35
	ds_read2st64_b32 v[14:15], v250 offset0:36 offset1:37
	ds_read2st64_b32 v[18:19], v250 offset0:38 offset1:39
	v_cndmask_b32_e32 v3, 0, v6, vcc
	v_cmp_gt_i32_e32 vcc, 0, v7
	v_xor_b32_e32 v0, -1, v5
	s_waitcnt lgkmcnt(5)
	v_and_b32_e32 v7, 0x7fffffff, v8
	v_cndmask_b32_e32 v6, v20, v4, vcc
	v_cmp_gt_i32_e32 vcc, 0, v5
	s_waitcnt lgkmcnt(2)
	v_xor_b32_e32 v20, -1, v10
	s_cmpk_gt_i32 s10, 0xfe
	v_cndmask_b32_e32 v0, v21, v0, vcc
	v_cmp_ge_i32_e32 vcc, s10, v227
	v_and_b32_e32 v21, 0x7fffffff, v9
	s_mov_b32 s11, 1
	v_cndmask_b32_e32 v4, 0, v0, vcc
	v_cmp_ge_i32_e32 vcc, s2, v162
	v_xor_b32_e32 v0, -1, v8
	s_mov_b32 s44, 1
	v_cndmask_b32_e32 v5, 0, v6, vcc
	v_and_b32_e32 v6, 0x7fffffff, v10
	v_pk_add_f32 v[6:7], v[6:7], 0 neg_lo:[1,1] neg_hi:[1,1]
	v_cmp_gt_i32_e32 vcc, 0, v10
	s_nop 1
	v_cndmask_b32_e32 v10, v6, v20, vcc
	v_cmp_gt_i32_e32 vcc, 0, v8
	v_and_b32_e32 v20, 0x7fffffff, v11
	v_xor_b32_e32 v8, -1, v11
	v_cndmask_b32_e32 v0, v7, v0, vcc
	v_cmp_ge_i32_e32 vcc, s10, v225
	v_pk_add_f32 v[20:21], v[20:21], 0 neg_lo:[1,1] neg_hi:[1,1]
	s_nop 0
	v_cndmask_b32_e32 v6, 0, v0, vcc
	v_cmp_ge_i32_e32 vcc, s2, v164
	v_xor_b32_e32 v0, -1, v9
	s_nop 0
	v_cndmask_b32_e32 v7, 0, v10, vcc
	v_cmp_gt_i32_e32 vcc, 0, v11
	v_and_b32_e32 v11, 0x7fffffff, v12
	s_nop 0
	v_cndmask_b32_e32 v10, v20, v8, vcc
	v_cmp_gt_i32_e32 vcc, 0, v9
	s_waitcnt lgkmcnt(1)
	v_xor_b32_e32 v20, -1, v14
	v_cndmask_b32_e32 v0, v21, v0, vcc
	v_cmp_ge_i32_e32 vcc, s10, v223
	v_and_b32_e32 v21, 0x7fffffff, v13
	s_nop 0
	v_cndmask_b32_e32 v8, 0, v0, vcc
	v_cmp_ge_i32_e32 vcc, s2, v166
	v_xor_b32_e32 v0, -1, v12
	s_nop 0
	v_cndmask_b32_e32 v9, 0, v10, vcc
	v_and_b32_e32 v10, 0x7fffffff, v14
	v_pk_add_f32 v[10:11], v[10:11], 0 neg_lo:[1,1] neg_hi:[1,1]
	v_cmp_gt_i32_e32 vcc, 0, v14
	s_nop 1
	v_cndmask_b32_e32 v14, v10, v20, vcc
	v_cmp_gt_i32_e32 vcc, 0, v12
	v_and_b32_e32 v20, 0x7fffffff, v15
	v_xor_b32_e32 v12, -1, v15
	v_cndmask_b32_e32 v0, v11, v0, vcc
	v_cmp_ge_i32_e32 vcc, s10, v221
	v_pk_add_f32 v[20:21], v[20:21], 0 neg_lo:[1,1] neg_hi:[1,1]
	s_nop 0
	v_cndmask_b32_e32 v10, 0, v0, vcc
	v_cmp_ge_i32_e32 vcc, s2, v168
	v_xor_b32_e32 v0, -1, v13
	s_nop 0
	v_cndmask_b32_e32 v11, 0, v14, vcc
	v_cmp_gt_i32_e32 vcc, 0, v15
	v_and_b32_e32 v15, 0x7fffffff, v16
	s_waitcnt lgkmcnt(0)
	v_and_b32_e32 v14, 0x7fffffff, v18
	v_cndmask_b32_e32 v12, v20, v12, vcc
	v_cmp_gt_i32_e32 vcc, 0, v13
	v_xor_b32_e32 v20, -1, v18
	v_pk_add_f32 v[14:15], v[14:15], 0 neg_lo:[1,1] neg_hi:[1,1]
	v_cndmask_b32_e32 v0, v21, v0, vcc
	v_cmp_ge_i32_e32 vcc, s10, v219
	v_and_b32_e32 v21, 0x7fffffff, v17
	s_nop 0
	v_cndmask_b32_e32 v13, 0, v0, vcc
	v_cmp_ge_i32_e32 vcc, s2, v170
	v_xor_b32_e32 v0, -1, v16
	s_nop 0
	v_cndmask_b32_e32 v12, 0, v12, vcc
	v_cmp_gt_i32_e32 vcc, 0, v18
	s_nop 1
	v_cndmask_b32_e32 v14, v14, v20, vcc
	v_cmp_gt_i32_e32 vcc, 0, v16
	v_and_b32_e32 v20, 0x7fffffff, v19
	v_xor_b32_e32 v16, -1, v19
	v_cndmask_b32_e32 v0, v15, v0, vcc
	v_cmp_ge_i32_e32 vcc, s10, v217
	v_pk_add_f32 v[20:21], v[20:21], 0 neg_lo:[1,1] neg_hi:[1,1]
	s_nop 0
	v_cndmask_b32_e32 v15, 0, v0, vcc
	v_cmp_ge_i32_e32 vcc, s2, v172
	v_xor_b32_e32 v0, -1, v17
	s_nop 0
	v_cndmask_b32_e32 v14, 0, v14, vcc
	v_cmp_gt_i32_e32 vcc, 0, v19
	s_nop 1
	v_cndmask_b32_e32 v16, v20, v16, vcc
	v_cmp_gt_i32_e32 vcc, 0, v17
	s_nop 1
	v_cndmask_b32_e32 v0, v21, v0, vcc
	ds_read2st64_b32 v[20:21], v250 offset0:8 offset1:9
	ds_read2st64_b32 v[22:23], v250 offset0:40 offset1:41
	ds_read2st64_b32 v[24:25], v250 offset0:10 offset1:11
	ds_read2st64_b32 v[28:29], v250 offset0:12 offset1:13
	ds_read2st64_b32 v[32:33], v250 offset0:14 offset1:15
	v_cmp_ge_i32_e32 vcc, s10, v215
	s_waitcnt lgkmcnt(4)
	v_and_b32_e32 v19, 0x7fffffff, v20
	s_waitcnt lgkmcnt(3)
	v_and_b32_e32 v18, 0x7fffffff, v22
	v_cndmask_b32_e32 v17, 0, v0, vcc
	v_cmp_ge_i32_e32 vcc, s2, v182
	v_xor_b32_e32 v36, -1, v22
	v_pk_add_f32 v[18:19], v[18:19], 0 neg_lo:[1,1] neg_hi:[1,1]
	v_cndmask_b32_e32 v16, 0, v16, vcc
	v_cmp_gt_i32_e32 vcc, 0, v22
	v_xor_b32_e32 v0, -1, v20
	v_and_b32_e32 v37, 0x7fffffff, v21
	v_cndmask_b32_e32 v18, v18, v36, vcc
	v_cmp_gt_i32_e32 vcc, 0, v20
	v_and_b32_e32 v36, 0x7fffffff, v23
	ds_read2st64_b32 v[26:27], v250 offset0:42 offset1:43
	ds_read2st64_b32 v[30:31], v250 offset0:44 offset1:45
	ds_read2st64_b32 v[34:35], v250 offset0:46 offset1:47
	v_cndmask_b32_e32 v0, v19, v0, vcc
	v_cmp_ge_i32_e32 vcc, s10, v213
	v_xor_b32_e32 v20, -1, v23
	v_pk_add_f32 v[36:37], v[36:37], 0 neg_lo:[1,1] neg_hi:[1,1]
	v_cndmask_b32_e32 v19, 0, v0, vcc
	v_cmp_ge_i32_e32 vcc, s2, v184
	v_xor_b32_e32 v0, -1, v21
	s_nop 0
	v_cndmask_b32_e32 v18, 0, v18, vcc
	v_cmp_gt_i32_e32 vcc, 0, v23
	s_nop 1
	v_cndmask_b32_e32 v20, v36, v20, vcc
	v_cmp_gt_i32_e32 vcc, 0, v21
	s_waitcnt lgkmcnt(2)
	v_and_b32_e32 v36, 0x7fffffff, v26
	v_cndmask_b32_e32 v0, v37, v0, vcc
	v_cmp_ge_i32_e32 vcc, s10, v211
	v_and_b32_e32 v37, 0x7fffffff, v24
	v_pk_add_f32 v[36:37], v[36:37], 0 neg_lo:[1,1] neg_hi:[1,1]
	v_cndmask_b32_e32 v22, 0, v0, vcc
	v_cmp_ge_i32_e32 vcc, s2, v186
	v_xor_b32_e32 v0, -1, v24
	s_nop 0
	v_cndmask_b32_e32 v21, 0, v20, vcc
	v_xor_b32_e32 v20, -1, v26
	v_cmp_gt_i32_e32 vcc, 0, v26
	s_nop 1
	v_cndmask_b32_e32 v20, v36, v20, vcc
	v_cmp_gt_i32_e32 vcc, 0, v24
	v_and_b32_e32 v36, 0x7fffffff, v27
	s_nop 0
	v_cndmask_b32_e32 v0, v37, v0, vcc
	v_cmp_ge_i32_e32 vcc, s10, v209
	v_and_b32_e32 v37, 0x7fffffff, v25
	v_pk_add_f32 v[36:37], v[36:37], 0 neg_lo:[1,1] neg_hi:[1,1]
	v_cndmask_b32_e32 v24, 0, v0, vcc
	v_cmp_ge_i32_e32 vcc, s2, v188
	v_xor_b32_e32 v0, -1, v25
	s_nop 0
	v_cndmask_b32_e32 v23, 0, v20, vcc
	v_xor_b32_e32 v20, -1, v27
	v_cmp_gt_i32_e32 vcc, 0, v27
	s_nop 1
	v_cndmask_b32_e32 v20, v36, v20, vcc
	v_cmp_gt_i32_e32 vcc, 0, v25
	s_waitcnt lgkmcnt(1)
	v_and_b32_e32 v36, 0x7fffffff, v30
	v_cndmask_b32_e32 v0, v37, v0, vcc
	v_cmp_ge_i32_e32 vcc, s10, v207
	v_and_b32_e32 v37, 0x7fffffff, v28
	v_pk_add_f32 v[36:37], v[36:37], 0 neg_lo:[1,1] neg_hi:[1,1]
	v_cndmask_b32_e32 v26, 0, v0, vcc
	v_cmp_ge_i32_e32 vcc, s2, v190
	v_xor_b32_e32 v0, -1, v28
	s_nop 0
	v_cndmask_b32_e32 v25, 0, v20, vcc
	v_xor_b32_e32 v20, -1, v30
	v_cmp_gt_i32_e32 vcc, 0, v30
	s_nop 1
	v_cndmask_b32_e32 v20, v36, v20, vcc
	v_cmp_gt_i32_e32 vcc, 0, v28
	v_and_b32_e32 v36, 0x7fffffff, v31
	s_nop 0
	v_cndmask_b32_e32 v0, v37, v0, vcc
	v_cmp_ge_i32_e32 vcc, s10, v205
	v_and_b32_e32 v37, 0x7fffffff, v29
	v_pk_add_f32 v[36:37], v[36:37], 0 neg_lo:[1,1] neg_hi:[1,1]
	v_cndmask_b32_e32 v28, 0, v0, vcc
	v_cmp_ge_i32_e32 vcc, s2, v192
	v_xor_b32_e32 v0, -1, v29
	s_nop 0
	v_cndmask_b32_e32 v27, 0, v20, vcc
	v_xor_b32_e32 v20, -1, v31
	v_cmp_gt_i32_e32 vcc, 0, v31
	s_nop 1
	v_cndmask_b32_e32 v20, v36, v20, vcc
	v_cmp_gt_i32_e32 vcc, 0, v29
	s_waitcnt lgkmcnt(0)
	v_and_b32_e32 v36, 0x7fffffff, v34
	v_cndmask_b32_e32 v0, v37, v0, vcc
	v_cmp_ge_i32_e32 vcc, s10, v203
	v_and_b32_e32 v37, 0x7fffffff, v32
	v_pk_add_f32 v[36:37], v[36:37], 0 neg_lo:[1,1] neg_hi:[1,1]
	v_cndmask_b32_e32 v30, 0, v0, vcc
	v_cmp_ge_i32_e32 vcc, s2, v194
	v_xor_b32_e32 v0, -1, v32
	s_nop 0
	v_cndmask_b32_e32 v29, 0, v20, vcc
	v_xor_b32_e32 v20, -1, v34
	v_cmp_gt_i32_e32 vcc, 0, v34
	s_nop 1
	v_cndmask_b32_e32 v20, v36, v20, vcc
	v_cmp_gt_i32_e32 vcc, 0, v32
	v_and_b32_e32 v36, 0x7fffffff, v35
	s_nop 0
	v_cndmask_b32_e32 v0, v37, v0, vcc
	v_cmp_ge_i32_e32 vcc, s10, v201
	v_and_b32_e32 v37, 0x7fffffff, v33
	v_pk_add_f32 v[36:37], v[36:37], 0 neg_lo:[1,1] neg_hi:[1,1]
	v_cndmask_b32_e32 v32, 0, v0, vcc
	v_cmp_ge_i32_e32 vcc, s2, v196
	v_xor_b32_e32 v0, -1, v33
	s_nop 0
	v_cndmask_b32_e32 v31, 0, v20, vcc
	v_xor_b32_e32 v20, -1, v35
	v_cmp_gt_i32_e32 vcc, 0, v35
	s_nop 1
	v_cndmask_b32_e32 v20, v36, v20, vcc
	v_cmp_gt_i32_e32 vcc, 0, v33
	s_nop 1
	v_cndmask_b32_e32 v0, v37, v0, vcc
	ds_read2st64_b32 v[34:35], v250 offset0:16 offset1:17
	ds_read2st64_b32 v[36:37], v250 offset0:48 offset1:49
	ds_read2st64_b32 v[44:45], v250 offset0:18 offset1:19
	ds_read2st64_b32 v[46:47], v250 offset0:20 offset1:21
	ds_read2st64_b32 v[48:49], v250 offset0:22 offset1:23
	v_cmp_ge_i32_e32 vcc, s10, v199
	s_waitcnt lgkmcnt(4)
	v_and_b32_e32 v39, 0x7fffffff, v34
	s_waitcnt lgkmcnt(3)
	v_and_b32_e32 v38, 0x7fffffff, v36
	v_cndmask_b32_e32 v33, 0, v0, vcc
	v_cmp_ge_i32_e32 vcc, s2, v198
	v_xor_b32_e32 v40, -1, v36
	v_pk_add_f32 v[38:39], v[38:39], 0 neg_lo:[1,1] neg_hi:[1,1]
	v_cndmask_b32_e32 v20, 0, v20, vcc
	v_cmp_gt_i32_e32 vcc, 0, v36
	v_xor_b32_e32 v0, -1, v34
	v_and_b32_e32 v41, 0x7fffffff, v35
	v_cndmask_b32_e32 v36, v38, v40, vcc
	v_cmp_gt_i32_e32 vcc, 0, v34
	v_and_b32_e32 v40, 0x7fffffff, v37
	v_pk_add_f32 v[40:41], v[40:41], 0 neg_lo:[1,1] neg_hi:[1,1]
	v_cndmask_b32_e32 v0, v39, v0, vcc
	v_cmp_ge_i32_e32 vcc, s10, v197
	ds_read2st64_b32 v[50:51], v250 offset0:50 offset1:51
	ds_read2st64_b32 v[52:53], v250 offset0:52 offset1:53
	ds_read2st64_b32 v[54:55], v250 offset0:54 offset1:55
	v_cndmask_b32_e32 v39, 0, v0, vcc
	v_cmp_ge_i32_e32 vcc, s2, v200
	v_xor_b32_e32 v0, -1, v35
	s_waitcnt lgkmcnt(2)
	v_xor_b32_e32 v38, -1, v50
	v_cndmask_b32_e32 v34, 0, v36, vcc
	v_xor_b32_e32 v36, -1, v37
	v_cmp_gt_i32_e32 vcc, 0, v37
	v_and_b32_e32 v37, 0x7fffffff, v44
	v_and_b32_e32 v57, 0x7fffffff, v45
	v_cndmask_b32_e32 v36, v40, v36, vcc
	v_cmp_gt_i32_e32 vcc, 0, v35
	v_and_b32_e32 v56, 0x7fffffff, v51
	v_pk_add_f32 v[56:57], v[56:57], 0 neg_lo:[1,1] neg_hi:[1,1]
	v_cndmask_b32_e32 v0, v41, v0, vcc
	v_cmp_ge_i32_e32 vcc, s10, v195
	s_waitcnt lgkmcnt(1)
	v_xor_b32_e32 v40, -1, v52
	v_xor_b32_e32 v42, -1, v53
	v_cndmask_b32_e32 v41, 0, v0, vcc
	v_cmp_ge_i32_e32 vcc, s2, v202
	v_xor_b32_e32 v0, -1, v44
	s_nop 0
	v_cndmask_b32_e32 v35, 0, v36, vcc
	v_and_b32_e32 v36, 0x7fffffff, v50
	v_pk_add_f32 v[36:37], v[36:37], 0 neg_lo:[1,1] neg_hi:[1,1]
	v_cmp_gt_i32_e32 vcc, 0, v50
	v_and_b32_e32 v50, 0x7fffffff, v53
	s_nop 0
	v_cndmask_b32_e32 v36, v36, v38, vcc
	v_cmp_gt_i32_e32 vcc, 0, v44
	v_and_b32_e32 v44, 0x7fffffff, v52
	v_xor_b32_e32 v38, -1, v46
	v_cndmask_b32_e32 v0, v37, v0, vcc
	v_cmp_ge_i32_e32 vcc, s10, v193
	v_xor_b32_e32 v37, -1, v51
	s_nop 0
	v_cndmask_b32_e32 v43, 0, v0, vcc
	v_cmp_ge_i32_e32 vcc, s2, v204
	v_xor_b32_e32 v0, -1, v45
	s_nop 0
	v_cndmask_b32_e32 v36, 0, v36, vcc
	v_cmp_gt_i32_e32 vcc, 0, v51
	v_and_b32_e32 v51, 0x7fffffff, v47
	v_pk_add_f32 v[50:51], v[50:51], 0 neg_lo:[1,1] neg_hi:[1,1]
	v_cndmask_b32_e32 v37, v56, v37, vcc
	v_cmp_gt_i32_e32 vcc, 0, v45
	v_and_b32_e32 v45, 0x7fffffff, v46
	v_pk_add_f32 v[44:45], v[44:45], 0 neg_lo:[1,1] neg_hi:[1,1]
	v_cndmask_b32_e32 v0, v57, v0, vcc
	v_cmp_ge_i32_e32 vcc, s10, v191
	s_nop 1
	v_cndmask_b32_e32 v0, 0, v0, vcc
	v_cmp_ge_i32_e32 vcc, s2, v206
	s_nop 1
	v_cndmask_b32_e32 v37, 0, v37, vcc
	v_cmp_gt_i32_e32 vcc, 0, v52
	s_nop 1
	v_cndmask_b32_e32 v40, v44, v40, vcc
	v_cmp_gt_i32_e32 vcc, 0, v46
	s_waitcnt lgkmcnt(0)
	v_xor_b32_e32 v44, -1, v54
	v_cndmask_b32_e32 v38, v45, v38, vcc
	v_cmp_ge_i32_e32 vcc, s10, v189
	s_nop 1
	v_cndmask_b32_e32 v45, 0, v38, vcc
	v_cmp_ge_i32_e32 vcc, s2, v208
	s_nop 1
	v_cndmask_b32_e32 v38, 0, v40, vcc
	v_cmp_gt_i32_e32 vcc, 0, v53
	v_xor_b32_e32 v40, -1, v47
	s_nop 0
	v_cndmask_b32_e32 v42, v50, v42, vcc
	v_cmp_gt_i32_e32 vcc, 0, v47
	v_and_b32_e32 v50, 0x7fffffff, v54
	s_nop 0
	v_cndmask_b32_e32 v40, v51, v40, vcc
	v_cmp_ge_i32_e32 vcc, s10, v187
	v_and_b32_e32 v51, 0x7fffffff, v48
	v_pk_add_f32 v[50:51], v[50:51], 0 neg_lo:[1,1] neg_hi:[1,1]
	v_cndmask_b32_e32 v46, 0, v40, vcc
	v_cmp_ge_i32_e32 vcc, s2, v210
	s_nop 1
	v_cndmask_b32_e32 v40, 0, v42, vcc
	v_cmp_gt_i32_e32 vcc, 0, v54
	v_xor_b32_e32 v42, -1, v48
	s_nop 0
	v_cndmask_b32_e32 v44, v50, v44, vcc
	v_cmp_gt_i32_e32 vcc, 0, v48
	v_and_b32_e32 v50, 0x7fffffff, v55
	v_xor_b32_e32 v48, -1, v55
	v_cndmask_b32_e32 v42, v51, v42, vcc
	v_cmp_ge_i32_e32 vcc, s10, v185
	v_and_b32_e32 v51, 0x7fffffff, v49
	v_pk_add_f32 v[50:51], v[50:51], 0 neg_lo:[1,1] neg_hi:[1,1]
	v_cndmask_b32_e32 v47, 0, v42, vcc
	v_cmp_ge_i32_e32 vcc, s2, v212
	s_nop 1
	v_cndmask_b32_e32 v42, 0, v44, vcc
	v_cmp_gt_i32_e32 vcc, 0, v55
	v_xor_b32_e32 v44, -1, v49
	s_nop 0
	v_cndmask_b32_e32 v50, v50, v48, vcc
	v_cmp_gt_i32_e32 vcc, 0, v49
	s_nop 1
	v_cndmask_b32_e32 v44, v51, v44, vcc
	v_cmp_ge_i32_e32 vcc, s10, v183
	s_nop 1
	v_cndmask_b32_e32 v48, 0, v44, vcc
	v_cmp_ge_i32_e32 vcc, s2, v214
	s_nop 1
	v_cndmask_b32_e32 v44, 0, v50, vcc
	ds_read2st64_b32 v[50:51], v250 offset0:24 offset1:25
	ds_read2st64_b32 v[52:53], v250 offset0:56 offset1:57
	ds_read2st64_b32 v[56:57], v250 offset0:26 offset1:27
	ds_read2st64_b32 v[60:61], v250 offset0:28 offset1:29
	ds_read2st64_b32 v[64:65], v250 offset0:30 offset1:31
	s_waitcnt lgkmcnt(4)
	v_and_b32_e32 v55, 0x7fffffff, v50
	s_waitcnt lgkmcnt(3)
	v_and_b32_e32 v54, 0x7fffffff, v52
	s_waitcnt vmcnt(0)
	v_xor_b32_e32 v68, -1, v52
	v_pk_add_f32 v[54:55], v[54:55], 0 neg_lo:[1,1] neg_hi:[1,1]
	v_cmp_gt_i32_e32 vcc, 0, v52
	v_xor_b32_e32 v49, -1, v50
	ds_read2st64_b32 v[58:59], v250 offset0:58 offset1:59
	ds_read2st64_b32 v[62:63], v250 offset0:60 offset1:61
	ds_read2st64_b32 v[66:67], v250 offset0:62 offset1:63
	v_cndmask_b32_e32 v54, v54, v68, vcc
	v_cmp_gt_i32_e32 vcc, 0, v50
	v_xor_b32_e32 v68, -1, v53
	v_xor_b32_e32 v50, -1, v51
	v_cndmask_b32_e32 v49, v55, v49, vcc
	v_cmp_ge_i32_e32 vcc, s10, v181
	v_and_b32_e32 v55, 0x7fffffff, v51
	s_waitcnt lgkmcnt(5)
	v_and_b32_e32 v69, 0x7fffffff, v56
	v_cndmask_b32_e32 v52, 0, v49, vcc
	v_cmp_ge_i32_e32 vcc, s2, v216
	s_nop 1
	v_cndmask_b32_e32 v49, 0, v54, vcc
	v_and_b32_e32 v54, 0x7fffffff, v53
	v_pk_add_f32 v[54:55], v[54:55], 0 neg_lo:[1,1] neg_hi:[1,1]
	v_cmp_gt_i32_e32 vcc, 0, v53
	s_nop 1
	v_cndmask_b32_e32 v53, v54, v68, vcc
	v_cmp_gt_i32_e32 vcc, 0, v51
	s_waitcnt lgkmcnt(2)
	v_and_b32_e32 v68, 0x7fffffff, v58
	v_pk_add_f32 v[68:69], v[68:69], 0 neg_lo:[1,1] neg_hi:[1,1]
	v_cndmask_b32_e32 v50, v55, v50, vcc
	v_cmp_ge_i32_e32 vcc, s10, v179
	v_xor_b32_e32 v51, -1, v56
	v_xor_b32_e32 v55, -1, v59
	v_cndmask_b32_e32 v54, 0, v50, vcc
	v_cmp_ge_i32_e32 vcc, s2, v218
	s_nop 1
	v_cndmask_b32_e32 v50, 0, v53, vcc
	v_xor_b32_e32 v53, -1, v58
	v_cmp_gt_i32_e32 vcc, 0, v58
	s_nop 1
	v_cndmask_b32_e32 v53, v68, v53, vcc
	v_cmp_gt_i32_e32 vcc, 0, v56
	v_and_b32_e32 v68, 0x7fffffff, v59
	s_nop 0
	v_cndmask_b32_e32 v51, v69, v51, vcc
	v_cmp_ge_i32_e32 vcc, s10, v173
	v_and_b32_e32 v69, 0x7fffffff, v57
	v_pk_add_f32 v[68:69], v[68:69], 0 neg_lo:[1,1] neg_hi:[1,1]
	v_cndmask_b32_e32 v56, 0, v51, vcc
	v_cmp_ge_i32_e32 vcc, s2, v220
	s_nop 1
	v_cndmask_b32_e32 v51, 0, v53, vcc
	v_cmp_gt_i32_e32 vcc, 0, v59
	v_xor_b32_e32 v53, -1, v57
	s_nop 0
	v_cndmask_b32_e32 v55, v68, v55, vcc
	v_cmp_gt_i32_e32 vcc, 0, v57
	s_waitcnt lgkmcnt(1)
	v_and_b32_e32 v68, 0x7fffffff, v62
	v_xor_b32_e32 v57, -1, v62
	v_cndmask_b32_e32 v53, v69, v53, vcc
	v_cmp_ge_i32_e32 vcc, s10, v171
	v_and_b32_e32 v69, 0x7fffffff, v60
	v_pk_add_f32 v[68:69], v[68:69], 0 neg_lo:[1,1] neg_hi:[1,1]
	v_cndmask_b32_e32 v58, 0, v53, vcc
	v_cmp_ge_i32_e32 vcc, s2, v222
	s_nop 1
	v_cndmask_b32_e32 v53, 0, v55, vcc
	v_cmp_gt_i32_e32 vcc, 0, v62
	v_xor_b32_e32 v55, -1, v60
	s_waitcnt lgkmcnt(0)
	v_and_b32_e32 v62, 0x7fffffff, v66
	v_cndmask_b32_e32 v57, v68, v57, vcc
	v_cmp_gt_i32_e32 vcc, 0, v60
	v_and_b32_e32 v68, 0x7fffffff, v63
	v_xor_b32_e32 v60, -1, v63
	v_cndmask_b32_e32 v55, v69, v55, vcc
	v_cmp_ge_i32_e32 vcc, s10, v169
	v_and_b32_e32 v69, 0x7fffffff, v61
	v_pk_add_f32 v[68:69], v[68:69], 0 neg_lo:[1,1] neg_hi:[1,1]
	v_cndmask_b32_e32 v59, 0, v55, vcc
	v_cmp_ge_i32_e32 vcc, s2, v224
	s_nop 1
	v_cndmask_b32_e32 v55, 0, v57, vcc
	v_cmp_gt_i32_e32 vcc, 0, v63
	v_xor_b32_e32 v57, -1, v61
	v_and_b32_e32 v63, 0x7fffffff, v64
	v_cndmask_b32_e32 v60, v68, v60, vcc
	v_cmp_gt_i32_e32 vcc, 0, v61
	v_xor_b32_e32 v68, -1, v66
	v_pk_add_f32 v[62:63], v[62:63], 0 neg_lo:[1,1] neg_hi:[1,1]
	v_cndmask_b32_e32 v57, v69, v57, vcc
	v_cmp_ge_i32_e32 vcc, s10, v167
	v_and_b32_e32 v69, 0x7fffffff, v65
	s_nop 0
	v_cndmask_b32_e32 v61, 0, v57, vcc
	v_cmp_ge_i32_e32 vcc, s2, v226
	s_nop 1
	v_cndmask_b32_e32 v57, 0, v60, vcc
	v_cmp_gt_i32_e32 vcc, 0, v66
	v_xor_b32_e32 v60, -1, v64
	s_nop 0
	v_cndmask_b32_e32 v62, v62, v68, vcc
	v_cmp_gt_i32_e32 vcc, 0, v64
	v_and_b32_e32 v68, 0x7fffffff, v67
	v_xor_b32_e32 v64, -1, v67
	v_cndmask_b32_e32 v60, v63, v60, vcc
	v_cmp_ge_i32_e32 vcc, s10, v165
	v_pk_add_f32 v[68:69], v[68:69], 0 neg_lo:[1,1] neg_hi:[1,1]
	s_nop 0
	v_cndmask_b32_e32 v63, 0, v60, vcc
	v_cmp_ge_i32_e32 vcc, s2, v228
	s_nop 1
	v_cndmask_b32_e32 v60, 0, v62, vcc
	v_cmp_gt_i32_e32 vcc, 0, v67
	v_xor_b32_e32 v62, -1, v65
	s_nop 0
	v_cndmask_b32_e32 v66, v68, v64, vcc
	v_cmp_gt_i32_e32 vcc, 0, v65
	s_nop 1
	v_cndmask_b32_e32 v62, v69, v62, vcc
	v_cmp_ge_i32_e32 vcc, s10, v163
	s_nop 1
	v_cndmask_b32_e32 v64, 0, v62, vcc
	v_cmp_ge_i32_e32 vcc, s2, v230
	s_nop 1
	v_cndmask_b32_e32 v62, 0, v66, vcc
	s_cbranch_scc0 .LBB0_133
	s_cmpk_gt_u32 s10, 0x1ff
	s_cselect_b64 s[0:1], -1, 0
	s_cmpk_gt_u32 s10, 0x3ff
	s_cselect_b64 s[8:9], -1, 0
	s_mov_b32 s6, 0
	s_cmpk_gt_u32 s10, 0x5ff
	s_mov_b32 s24, 31
	s_mov_b32 s98, 0
	s_mov_b32 s99, 0
	s_cselect_b64 s[10:11], -1, 0
	s_mov_b32 s7, s6
	s_branch .LBB0_126
